# GEMM epilogue stores sc0 sc1 nt
# baseline (speedup 1.0000x reference)
; __device__ __forceinline__ unsigned cvt_pk_bf16(float lo, float hi) { unsigned r; asm volatile("v_cvt_pk_bf16_f32 %0, %1, %2" : "=v"(r) : "v"(lo), "v"(hi)); return r; }
;     __device__ __forceinline__ void operator()(const f32x4 (&acc)[2][2][4][2], const Unit& u, int wr, int wc, int fr, int fq) const {
;         const int row0 = u.pm * BM + wr * 64 + fr; int colt = u.pn * BM; bf16_t* base = O;
;         float sc = 1.f; if (split_cols) { const int t = colt / split_cols; base += (size_t)t * split_stride; colt -= t * split_cols; if (t == 0) sc = scale0; }
;         const int col0 = colt + wc * 32 + 8 * fq, bcol0 = u.pn * BM + wc * 32 + 8 * fq;
;         f32x4 bv[2][2];
; #pragma unroll
;         for (int bj = 0; bj < 2; ++bj)
; #pragma unroll
;             for (int n = 0; n < 2; ++n) bv[bj][n] = bias ? *(const f32x4*)(bias + bcol0 + bj * HALF + 4 * n) : (f32x4){0.f, 0.f, 0.f, 0.f};
; #pragma unroll
;         for (int ai = 0; ai < 2; ++ai)
; #pragma unroll
;             for (int m = 0; m < 4; ++m) { bf16_t* rowp = base + (size_t)(row0 + ai * HALF + m * 16) * ldc + col0;
; #pragma unroll
;                 for (int bj = 0; bj < 2; ++bj) { f32x4 v0 = acc[ai][bj][m][0] + bv[bj][0], v1 = acc[ai][bj][m][1] + bv[bj][1];
;                     if (ACT == 1) { f32x2 a = gelu_pk((f32x2){v0[0], v0[1]}), b = gelu_pk((f32x2){v0[2], v0[3]}), c = gelu_pk((f32x2){v1[0], v1[1]}), d = gelu_pk((f32x2){v1[2], v1[3]});
;                         v0 = (f32x4){a.x, a.y, b.x, b.y}; v1 = (f32x4){c.x, c.y, d.x, d.y}; }
;                     v0 = v0 * sc; v1 = v1 * sc; u32x4 w; w.x = cvt_pk_bf16(v0[0], v0[1]); w.y = cvt_pk_bf16(v0[2], v0[3]); w.z = cvt_pk_bf16(v1[0], v1[1]); w.w = cvt_pk_bf16(v1[2], v1[3]);
;                     *(u32x4*)(rowp + bj * HALF) = w; } }
.LBB0_377:
	s_ashr_i32 s69, s68, 31
	s_lshl_b32 s12, s68, 8
	s_lshl_b64 s[6:7], s[68:69], 23
	s_and_b64 s[8:9], s[98:99], exec
	s_cselect_b32 s6, 0, s6
	s_cselect_b32 s7, 0, s7
	s_add_u32 s6, s30, s6
	s_addc_u32 s7, s31, s7
	s_and_b64 s[8:9], s[98:99], exec
	s_cselect_b32 s8, s12, 0
	v_lshl_add_u32 v147, s44, 8, v1
	v_or_b32_e32 v142, s8, v145
	v_ashrrev_i32_e32 v143, 31, v142
	v_ashrrev_i32_e32 v148, 31, v147
	v_lshl_add_u64 v[142:143], v[142:143], 1, s[6:7]
	v_mul_lo_u32 v152, s57, v148
	v_mad_u64_u32 v[148:149], s[6:7], s57, v147, 0
	v_add_u32_e32 v149, v149, v152
	v_lshl_add_u64 v[148:149], v[148:149], 1, v[142:143]
	v_pk_add_f32 v[128:129], v[128:129], 0 op_sel_hi:[1,0]
	v_pk_add_f32 v[126:127], v[126:127], 0 op_sel_hi:[1,0]
	v_pk_add_f32 v[150:151], v[124:125], 0 op_sel_hi:[1,0]
	v_pk_add_f32 v[124:125], v[122:123], 0 op_sel_hi:[1,0]
	v_cvt_pk_bf16_f32 v122, v126, v127
	v_cvt_pk_bf16_f32 v123, v128, v129
	v_pk_add_f32 v[118:119], v[118:119], 0 op_sel_hi:[1,0]
	v_cvt_pk_bf16_f32 v124, v124, v125
	v_cvt_pk_bf16_f32 v125, v150, v151
	global_store_dwordx4 v[148:149], v[122:125], off sc0 sc1 nt
	v_pk_add_f32 v[120:121], v[120:121], 0 op_sel_hi:[1,0]
	v_pk_add_f32 v[114:115], v[114:115], 0 op_sel_hi:[1,0]
	v_pk_add_f32 v[122:123], v[112:113], 0 op_sel_hi:[1,0]
	v_pk_add_f32 v[112:113], v[110:111], 0 op_sel_hi:[1,0]
	v_cvt_pk_bf16_f32 v110, v118, v119
	v_cvt_pk_bf16_f32 v111, v120, v121
	v_pk_add_f32 v[102:103], v[102:103], 0 op_sel_hi:[1,0]
	v_cvt_pk_bf16_f32 v112, v112, v113
	v_cvt_pk_bf16_f32 v113, v122, v123
	global_store_dwordx4 v[148:149], v[110:113], off offset:256 sc0 sc1 nt
	v_pk_add_f32 v[104:105], v[104:105], 0 op_sel_hi:[1,0]
	v_pk_add_f32 v[98:99], v[98:99], 0 op_sel_hi:[1,0]
	v_or_b32_e32 v110, 16, v147
	v_mad_u64_u32 v[110:111], s[6:7], s57, v110, 0
	v_add_u32_e32 v111, v111, v152
	v_lshl_add_u64 v[110:111], v[110:111], 1, v[142:143]
	v_pk_add_f32 v[112:113], v[116:117], 0 op_sel_hi:[1,0]
	v_pk_add_f32 v[116:117], v[108:109], 0 op_sel_hi:[1,0]
	v_pk_add_f32 v[108:109], v[106:107], 0 op_sel_hi:[1,0]
	v_cvt_pk_bf16_f32 v106, v114, v115
	v_cvt_pk_bf16_f32 v107, v112, v113
	v_pk_add_f32 v[86:87], v[86:87], 0 op_sel_hi:[1,0]
	v_cvt_pk_bf16_f32 v108, v108, v109
	v_cvt_pk_bf16_f32 v109, v116, v117
	global_store_dwordx4 v[110:111], v[106:109], off sc0 sc1 nt
	v_pk_add_f32 v[88:89], v[88:89], 0 op_sel_hi:[1,0]
	v_pk_add_f32 v[82:83], v[82:83], 0 op_sel_hi:[1,0]
	v_pk_add_f32 v[106:107], v[96:97], 0 op_sel_hi:[1,0]
	v_pk_add_f32 v[96:97], v[94:95], 0 op_sel_hi:[1,0]
	v_cvt_pk_bf16_f32 v94, v102, v103
	v_cvt_pk_bf16_f32 v95, v104, v105
	v_pk_add_f32 v[70:71], v[70:71], 0 op_sel_hi:[1,0]
	v_cvt_pk_bf16_f32 v96, v96, v97
	v_cvt_pk_bf16_f32 v97, v106, v107
	global_store_dwordx4 v[110:111], v[94:97], off offset:256 sc0 sc1 nt
	v_pk_add_f32 v[72:73], v[72:73], 0 op_sel_hi:[1,0]
	v_pk_add_f32 v[64:65], v[64:65], 0 op_sel_hi:[1,0]
	v_or_b32_e32 v94, 32, v147
	v_mad_u64_u32 v[94:95], s[6:7], s57, v94, 0
	v_add_u32_e32 v95, v95, v152
	v_lshl_add_u64 v[94:95], v[94:95], 1, v[142:143]
	v_pk_add_f32 v[96:97], v[100:101], 0 op_sel_hi:[1,0]
	v_pk_add_f32 v[100:101], v[92:93], 0 op_sel_hi:[1,0]
	v_pk_add_f32 v[92:93], v[90:91], 0 op_sel_hi:[1,0]
	v_cvt_pk_bf16_f32 v90, v98, v99
	v_cvt_pk_bf16_f32 v91, v96, v97
	v_pk_add_f32 v[62:63], v[62:63], 0 op_sel_hi:[1,0]
	v_cvt_pk_bf16_f32 v92, v92, v93
	v_cvt_pk_bf16_f32 v93, v100, v101
	global_store_dwordx4 v[94:95], v[90:93], off sc0 sc1 nt
	v_pk_add_f32 v[54:55], v[54:55], 0 op_sel_hi:[1,0]
	v_pk_add_f32 v[56:57], v[56:57], 0 op_sel_hi:[1,0]
	v_pk_add_f32 v[90:91], v[80:81], 0 op_sel_hi:[1,0]
	v_pk_add_f32 v[80:81], v[78:79], 0 op_sel_hi:[1,0]
	v_cvt_pk_bf16_f32 v78, v86, v87
	v_cvt_pk_bf16_f32 v79, v88, v89
	v_pk_add_f32 v[48:49], v[48:49], 0 op_sel_hi:[1,0]
	v_cvt_pk_bf16_f32 v80, v80, v81
	v_cvt_pk_bf16_f32 v81, v90, v91
	global_store_dwordx4 v[94:95], v[78:81], off offset:256 sc0 sc1 nt
	v_pk_add_f32 v[46:47], v[46:47], 0 op_sel_hi:[1,0]
	v_pk_add_f32 v[38:39], v[38:39], 0 op_sel_hi:[1,0]
	v_or_b32_e32 v78, 48, v147
	v_mad_u64_u32 v[78:79], s[6:7], s57, v78, 0
	v_add_u32_e32 v79, v79, v152
	v_lshl_add_u64 v[78:79], v[78:79], 1, v[142:143]
	v_pk_add_f32 v[80:81], v[84:85], 0 op_sel_hi:[1,0]
	v_pk_add_f32 v[84:85], v[76:77], 0 op_sel_hi:[1,0]
	v_pk_add_f32 v[76:77], v[74:75], 0 op_sel_hi:[1,0]
	v_cvt_pk_bf16_f32 v74, v82, v83
	v_cvt_pk_bf16_f32 v75, v80, v81
	v_pk_add_f32 v[40:41], v[40:41], 0 op_sel_hi:[1,0]
	v_cvt_pk_bf16_f32 v76, v76, v77
; __device__ __forceinline__ unsigned cvt_pk_bf16(float lo, float hi) { unsigned r; asm volatile("v_cvt_pk_bf16_f32 %0, %1, %2" : "=v"(r) : "v"(lo), "v"(hi)); return r; }
; #define PG8_BAR __builtin_amdgcn_s_barrier()
;     __device__ __forceinline__ void operator()(const f32x4 (&acc)[2][2][4][2], const Unit& u, int wr, int wc, int fr, int fq) const {
;     ...
;             for (int m = 0; m < 4; ++m) { bf16_t* rowp = base + (size_t)(row0 + ai * HALF + m * 16) * ldc + col0;
; #pragma unroll
;                 for (int bj = 0; bj < 2; ++bj) { f32x4 v0 = acc[ai][bj][m][0] + bv[bj][0], v1 = acc[ai][bj][m][1] + bv[bj][1];
;                     if (ACT == 1) { f32x2 a = gelu_pk((f32x2){v0[0], v0[1]}), b = gelu_pk((f32x2){v0[2], v0[3]}), c = gelu_pk((f32x2){v1[0], v1[1]}), d = gelu_pk((f32x2){v1[2], v1[3]});
;                         v0 = (f32x4){a.x, a.y, b.x, b.y}; v1 = (f32x4){c.x, c.y, d.x, d.y}; }
;                     v0 = v0 * sc; v1 = v1 * sc; u32x4 w; w.x = cvt_pk_bf16(v0[0], v0[1]); w.y = cvt_pk_bf16(v0[2], v0[3]); w.z = cvt_pk_bf16(v1[0], v1[1]); w.w = cvt_pk_bf16(v1[2], v1[3]);
;                     *(u32x4*)(rowp + bj * HALF) = w; } }
; template <class Epi, class Sched, bool ALIGN_EPI = false, bool SP2 = false>
; __device__ __forceinline__ void gemm_phase(PG8_LAS unsigned char* lds, const Gemm g, const Sched& S, const Epi& E) {
;     ...
;         if (!has_next) break;
; #pragma unroll
;         for (int a = 0; a < 2; ++a)
; #pragma unroll
;             for (int b = 0; b < 2; ++b)
; #pragma unroll
;                 for (int m = 0; m < 4; ++m)
; #pragma unroll
;                     for (int n = 0; n < 2; ++n) acc[a][b][m][n] = (f32x4){0.f, 0.f, 0.f, 0.f};
;         cur = nxt; cA = nA; cB = nB; ++ui;
;         if constexpr (ALIGN_EPI) { if (wr == 1) PG8_BAR; }
	v_cvt_pk_bf16_f32 v77, v84, v85
	global_store_dwordx4 v[78:79], v[74:77], off sc0 sc1 nt
	v_pk_add_f32 v[32:33], v[32:33], 0 op_sel_hi:[1,0]
	v_pk_add_f32 v[30:31], v[30:31], 0 op_sel_hi:[1,0]
	v_pk_add_f32 v[74:75], v[68:69], 0 op_sel_hi:[1,0]
	v_pk_add_f32 v[68:69], v[66:67], 0 op_sel_hi:[1,0]
	v_cvt_pk_bf16_f32 v66, v70, v71
	v_cvt_pk_bf16_f32 v67, v72, v73
	v_pk_add_f32 v[22:23], v[22:23], 0 op_sel_hi:[1,0]
	v_cvt_pk_bf16_f32 v68, v68, v69
	v_cvt_pk_bf16_f32 v69, v74, v75
	global_store_dwordx4 v[78:79], v[66:69], off offset:256 sc0 sc1 nt
	v_pk_add_f32 v[24:25], v[24:25], 0 op_sel_hi:[1,0]
	v_pk_add_f32 v[16:17], v[16:17], 0 op_sel_hi:[1,0]
	v_add_u32_e32 v66, 0x80, v147
	v_ashrrev_i32_e32 v69, 31, v66
	v_mad_u64_u32 v[66:67], s[6:7], s57, v66, 0
	v_mov_b32_e32 v68, v67
	v_mad_u64_u32 v[68:69], s[6:7], s57, v69, v[68:69]
	v_mov_b32_e32 v67, v68
	v_lshl_add_u64 v[66:67], v[66:67], 1, v[142:143]
	v_pk_add_f32 v[68:69], v[60:61], 0 op_sel_hi:[1,0]
	v_pk_add_f32 v[60:61], v[58:59], 0 op_sel_hi:[1,0]
	v_cvt_pk_bf16_f32 v58, v62, v63
	v_cvt_pk_bf16_f32 v59, v64, v65
	v_pk_add_f32 v[14:15], v[14:15], 0 op_sel_hi:[1,0]
	v_cvt_pk_bf16_f32 v60, v60, v61
	v_cvt_pk_bf16_f32 v61, v68, v69
	global_store_dwordx4 v[66:67], v[58:61], off sc0 sc1 nt
	s_andn2_b64 vcc, exec, s[40:41]
	v_pk_add_f32 v[8:9], v[8:9], 0 op_sel_hi:[1,0]
	v_pk_add_f32 v[58:59], v[52:53], 0 op_sel_hi:[1,0]
	v_pk_add_f32 v[52:53], v[50:51], 0 op_sel_hi:[1,0]
	v_cvt_pk_bf16_f32 v50, v54, v55
	v_cvt_pk_bf16_f32 v51, v56, v57
	v_pk_add_f32 v[6:7], v[6:7], 0 op_sel_hi:[1,0]
	v_cvt_pk_bf16_f32 v52, v52, v53
	v_cvt_pk_bf16_f32 v53, v58, v59
	global_store_dwordx4 v[66:67], v[50:53], off offset:256 sc0 sc1 nt
	s_nop 1
	v_add_u32_e32 v50, 0x90, v147
	v_ashrrev_i32_e32 v53, 31, v50
	v_mad_u64_u32 v[50:51], s[6:7], s57, v50, 0
	v_mov_b32_e32 v52, v51
	v_mad_u64_u32 v[52:53], s[6:7], s57, v53, v[52:53]
	v_mov_b32_e32 v51, v52
	v_lshl_add_u64 v[50:51], v[50:51], 1, v[142:143]
	v_pk_add_f32 v[52:53], v[44:45], 0 op_sel_hi:[1,0]
	v_pk_add_f32 v[44:45], v[42:43], 0 op_sel_hi:[1,0]
	v_cvt_pk_bf16_f32 v42, v46, v47
	v_cvt_pk_bf16_f32 v43, v48, v49
	s_nop 0
	v_cvt_pk_bf16_f32 v44, v44, v45
	v_cvt_pk_bf16_f32 v45, v52, v53
	global_store_dwordx4 v[50:51], v[42:45], off sc0 sc1 nt
	s_nop 1
	v_pk_add_f32 v[42:43], v[36:37], 0 op_sel_hi:[1,0]
	v_pk_add_f32 v[36:37], v[34:35], 0 op_sel_hi:[1,0]
	v_cvt_pk_bf16_f32 v34, v38, v39
	v_cvt_pk_bf16_f32 v35, v40, v41
	s_nop 0
	v_cvt_pk_bf16_f32 v36, v36, v37
	v_cvt_pk_bf16_f32 v37, v42, v43
	global_store_dwordx4 v[50:51], v[34:37], off offset:256 sc0 sc1 nt
	s_nop 1
	v_add_u32_e32 v34, 0xa0, v147
	v_ashrrev_i32_e32 v37, 31, v34
	v_mad_u64_u32 v[34:35], s[6:7], s57, v34, 0
	v_mov_b32_e32 v36, v35
	v_mad_u64_u32 v[36:37], s[6:7], s57, v37, v[36:37]
	v_mov_b32_e32 v35, v36
	v_lshl_add_u64 v[34:35], v[34:35], 1, v[142:143]
	v_pk_add_f32 v[36:37], v[28:29], 0 op_sel_hi:[1,0]
	v_pk_add_f32 v[28:29], v[26:27], 0 op_sel_hi:[1,0]
	v_cvt_pk_bf16_f32 v26, v30, v31
	v_cvt_pk_bf16_f32 v27, v32, v33
	s_nop 0
	v_cvt_pk_bf16_f32 v28, v28, v29
	v_cvt_pk_bf16_f32 v29, v36, v37
	global_store_dwordx4 v[34:35], v[26:29], off sc0 sc1 nt
	s_nop 1
	v_pk_add_f32 v[26:27], v[20:21], 0 op_sel_hi:[1,0]
	v_pk_add_f32 v[20:21], v[18:19], 0 op_sel_hi:[1,0]
	v_cvt_pk_bf16_f32 v18, v22, v23
	v_cvt_pk_bf16_f32 v19, v24, v25
	s_nop 0
	v_cvt_pk_bf16_f32 v20, v20, v21
	v_cvt_pk_bf16_f32 v21, v26, v27
	global_store_dwordx4 v[34:35], v[18:21], off offset:256 sc0 sc1 nt
	s_nop 1
	v_add_u32_e32 v18, 0xb0, v147
	v_ashrrev_i32_e32 v21, 31, v18
	v_mad_u64_u32 v[18:19], s[6:7], s57, v18, 0
	v_mov_b32_e32 v20, v19
	v_mad_u64_u32 v[20:21], s[6:7], s57, v21, v[20:21]
	v_mov_b32_e32 v19, v20
	v_lshl_add_u64 v[18:19], v[18:19], 1, v[142:143]
	v_pk_add_f32 v[20:21], v[12:13], 0 op_sel_hi:[1,0]
	v_pk_add_f32 v[12:13], v[10:11], 0 op_sel_hi:[1,0]
	v_cvt_pk_bf16_f32 v10, v14, v15
	v_cvt_pk_bf16_f32 v11, v16, v17
	s_mov_b64 s[6:7], -1
	v_cvt_pk_bf16_f32 v12, v12, v13
	v_cvt_pk_bf16_f32 v13, v20, v21
	global_store_dwordx4 v[18:19], v[10:13], off sc0 sc1 nt
	s_nop 1
	v_pk_add_f32 v[10:11], v[4:5], 0 op_sel_hi:[1,0]
	v_pk_add_f32 v[4:5], v[2:3], 0 op_sel_hi:[1,0]
	v_cvt_pk_bf16_f32 v2, v6, v7
	v_cvt_pk_bf16_f32 v3, v8, v9
	s_nop 0
	v_cvt_pk_bf16_f32 v4, v4, v5
	v_cvt_pk_bf16_f32 v5, v10, v11
	global_store_dwordx4 v[18:19], v[2:5], off offset:256 sc0 sc1 nt
	s_cbranch_vccnz .LBB0_368
	s_andn2_b64 vcc, exec, s[84:85]
	s_cbranch_vccnz .LBB0_367
	s_barrier
	s_branch .LBB0_367
